# attention epilogue: four gate loads per query tile issued together with counted waits (was load-wait-store chain), on top of max-tree
# speedup vs baseline: 1.0115x; 1.0115x over previous
.LBB0_201:
	v_and_b32_e32 v1, 64, v220
	v_xor_b32_e32 v0, 16, v220
	v_add_u32_e32 v1, 64, v1
	v_cmp_lt_i32_e32 vcc, v0, v1
	v_readlane_b32 s0, v255, 31
	v_readlane_b32 s70, v254, 6
	v_cndmask_b32_e32 v0, v220, v0, vcc
	s_waitcnt vmcnt(0)
	v_lshlrev_b32_e32 v44, 2, v0
	v_xor_b32_e32 v0, 32, v220
	v_cmp_lt_i32_e32 vcc, v0, v1
	v_or_b32_e32 v42, s0, v165
	v_readlane_b32 s0, v255, 32
	v_cndmask_b32_e32 v0, v220, v0, vcc
	v_lshlrev_b32_e32 v3, 2, v0
	ds_bpermute_b32 v0, v44, v138
	v_lshl_or_b32 v8, v166, 2, s0
	v_readlane_b32 s71, v254, 7
	s_movk_i32 s77, 0x1c00
	v_ashrrev_i32_e32 v43, 31, v42
	s_waitcnt lgkmcnt(0)
	v_add_f32_e32 v0, v138, v0
	ds_bpermute_b32 v1, v3, v0
	v_readlane_b32 s34, v255, 29
	v_readlane_b32 s68, v254, 5
	v_readlane_b32 s69, v254, 8
	v_readlane_b32 s72, v254, 9
	s_waitcnt lgkmcnt(0)
	v_add_f32_e32 v0, v0, v1
	v_div_scale_f32 v1, s[0:1], v0, v0, 1.0
	v_rcp_f32_e32 v2, v1
	v_readlane_b32 s73, v254, 10
	v_readlane_b32 s74, v254, 11
	v_readlane_b32 s75, v254, 12
	v_fma_f32 v4, -v1, v2, 1.0
	v_fmac_f32_e32 v2, v4, v2
	v_div_scale_f32 v4, vcc, 1.0, v0, 1.0
	v_mul_f32_e32 v5, v4, v2
	v_fma_f32 v6, -v1, v5, v4
	v_fmac_f32_e32 v5, v6, v2
	v_fma_f32 v1, -v1, v5, v4
	v_div_fmas_f32 v1, v1, v2, v5
	v_div_fixup_f32 v2, v1, v0, 1.0
	v_mov_b64_e32 v[0:1], s[70:71]
	v_mad_i64_i32 v[0:1], s[0:1], v42, s77, v[0:1]
	s_mov_b64 s[0:1], 0x1000
	s_nop 0
	v_lshl_add_u64 v[6:7], v[0:1], 0, s[0:1]
	v_lshlrev_b32_e32 v4, 1, v8
	v_mov_b32_e32 v5, v9
	v_lshl_add_u64 v[46:47], v[6:7], 0, v[4:5]
	v_mov_b64_e32 v[176:177], v[46:47]
	global_load_dwordx2 v[46:47], v[46:47], off
	global_load_dwordx2 v[178:179], v[176:177], off offset:32
	global_load_dwordx2 v[180:181], v[176:177], off offset:64
	global_load_dwordx2 v[182:183], v[176:177], off offset:96
	v_lshlrev_b64 v[0:1], 11, v[42:43]
	v_readlane_b32 s0, v251, 10
	v_readlane_b32 s1, v251, 11
	v_readlane_b32 s2, v251, 12
	v_readlane_b32 s3, v251, 13
	s_mov_b64 s[0:1], 0xb00200
	v_pk_mul_f32 v[38:39], v[38:39], v[2:3] op_sel_hi:[1,0]
	v_lshl_add_u64 v[0:1], s[2:3], 0, v[0:1]
	v_lshl_add_u64 v[0:1], v[0:1], 0, s[0:1]
	v_pk_mul_f32 v[40:41], v[40:41], v[2:3] op_sel_hi:[1,0]
	v_lshl_add_u64 v[4:5], v[0:1], 0, v[4:5]
	v_pk_mul_f32 v[34:35], v[34:35], v[2:3] op_sel_hi:[1,0]
	v_pk_mul_f32 v[36:37], v[36:37], v[2:3] op_sel_hi:[1,0]
	v_pk_mul_f32 v[30:31], v[30:31], v[2:3] op_sel_hi:[1,0]
	v_pk_mul_f32 v[32:33], v[32:33], v[2:3] op_sel_hi:[1,0]
	v_pk_mul_f32 v[26:27], v[26:27], v[2:3] op_sel_hi:[1,0]
	v_pk_mul_f32 v[28:29], v[28:29], v[2:3] op_sel_hi:[1,0]
	v_readlane_b32 s76, v254, 13
	v_readlane_b32 s35, v255, 30
	s_waitcnt vmcnt(3)
	v_lshlrev_b32_e32 v43, 16, v46
	v_and_b32_e32 v45, 0xffff0000, v46
	v_mul_f32_e32 v46, 0xbfb8aa3b, v43
	v_exp_f32_e32 v48, v46
	v_mul_f32_e32 v46, 0xbfb8aa3b, v45
	v_exp_f32_e32 v49, v46
	s_nop 0
	v_pk_add_f32 v[48:49], v[48:49], 1.0 op_sel_hi:[1,0]
	s_nop 0
	v_div_scale_f32 v46, s[0:1], v49, v49, v45
	v_rcp_f32_e32 v50, v46
	s_nop 0
	v_fma_f32 v51, -v46, v50, 1.0
	v_fmac_f32_e32 v50, v51, v50
	v_div_scale_f32 v51, vcc, v45, v49, v45
	v_mul_f32_e32 v52, v51, v50
	v_fma_f32 v53, -v46, v52, v51
	v_fmac_f32_e32 v52, v53, v50
	v_fma_f32 v46, -v46, v52, v51
	v_div_fmas_f32 v46, v46, v50, v52
	v_div_fixup_f32 v49, v46, v49, v45
	v_div_scale_f32 v45, s[0:1], v48, v48, v43
	v_rcp_f32_e32 v46, v45
	s_nop 0
	v_fma_f32 v50, -v45, v46, 1.0
	v_fmac_f32_e32 v46, v50, v46
	v_div_scale_f32 v50, vcc, v43, v48, v43
	v_mul_f32_e32 v51, v50, v46
	v_fma_f32 v52, -v45, v51, v50
	v_fmac_f32_e32 v51, v52, v46
	v_fma_f32 v45, -v45, v51, v50
	v_div_fmas_f32 v45, v45, v46, v51
	v_div_fixup_f32 v48, v45, v48, v43
	v_lshlrev_b32_e32 v43, 16, v47
	v_and_b32_e32 v45, 0xffff0000, v47
	v_mul_f32_e32 v46, 0xbfb8aa3b, v43
	v_mul_f32_e32 v47, 0xbfb8aa3b, v45
	v_exp_f32_e32 v46, v46
	v_exp_f32_e32 v47, v47
	v_pk_mul_f32 v[38:39], v[38:39], v[48:49]
	v_pk_add_f32 v[46:47], v[46:47], 1.0 op_sel_hi:[1,0]
	s_nop 0
	v_div_scale_f32 v48, s[0:1], v47, v47, v45
	v_rcp_f32_e32 v49, v48
	v_cvt_pk_bf16_f32 v38, v38, v39
	v_fma_f32 v50, -v48, v49, 1.0
	v_fmac_f32_e32 v49, v50, v49
	v_div_scale_f32 v50, vcc, v45, v47, v45
	v_mul_f32_e32 v51, v50, v49
	v_fma_f32 v52, -v48, v51, v50
	v_fmac_f32_e32 v51, v52, v49
	v_fma_f32 v48, -v48, v51, v50
	v_div_fmas_f32 v48, v48, v49, v51
	v_div_fixup_f32 v47, v48, v47, v45
	v_div_scale_f32 v45, s[0:1], v46, v46, v43
	v_rcp_f32_e32 v48, v45
	s_nop 0
	v_fma_f32 v49, -v45, v48, 1.0
	v_fmac_f32_e32 v48, v49, v48
	v_div_scale_f32 v49, vcc, v43, v46, v43
	v_mul_f32_e32 v50, v49, v48
	v_fma_f32 v51, -v45, v50, v49
	v_fmac_f32_e32 v50, v51, v48
	v_fma_f32 v45, -v45, v50, v49
	v_div_fmas_f32 v45, v45, v48, v50
	v_div_fixup_f32 v46, v45, v46, v43
	v_pk_mul_f32 v[40:41], v[40:41], v[46:47]
	s_nop 0
	v_cvt_pk_bf16_f32 v39, v40, v41
	global_store_dwordx2 v[4:5], v[38:39], off
	v_or_b32_e32 v38, 16, v8
	v_lshlrev_b32_e32 v4, 1, v38
	v_mov_b32_e32 v5, v9
	v_lshl_add_u64 v[40:41], v[6:7], 0, v[4:5]
	s_waitcnt vmcnt(3)
	v_mov_b64_e32 v[40:41], v[178:179]
	v_lshl_add_u64 v[4:5], v[0:1], 0, v[4:5]
	v_mov_b32_e32 v39, v9
	s_nop 0
	v_lshlrev_b32_e32 v43, 16, v40
	v_and_b32_e32 v40, 0xffff0000, v40
	v_mul_f32_e32 v45, 0xbfb8aa3b, v43
	v_exp_f32_e32 v46, v45
	v_mul_f32_e32 v45, 0xbfb8aa3b, v40
	v_exp_f32_e32 v47, v45
	s_nop 0
	v_pk_add_f32 v[46:47], v[46:47], 1.0 op_sel_hi:[1,0]
	s_nop 0
	v_div_scale_f32 v45, s[0:1], v47, v47, v40
	v_rcp_f32_e32 v48, v45
	s_nop 0
	v_fma_f32 v49, -v45, v48, 1.0
	v_fmac_f32_e32 v48, v49, v48
	v_div_scale_f32 v49, vcc, v40, v47, v40
	v_mul_f32_e32 v50, v49, v48
	v_fma_f32 v51, -v45, v50, v49
	v_fmac_f32_e32 v50, v51, v48
	v_fma_f32 v45, -v45, v50, v49
	v_div_fmas_f32 v45, v45, v48, v50
	v_div_fixup_f32 v47, v45, v47, v40
	v_div_scale_f32 v40, s[0:1], v46, v46, v43
	v_rcp_f32_e32 v45, v40
	s_nop 0
	v_fma_f32 v48, -v40, v45, 1.0
	v_fmac_f32_e32 v45, v48, v45
	v_div_scale_f32 v48, vcc, v43, v46, v43
	v_mul_f32_e32 v49, v48, v45
	v_fma_f32 v50, -v40, v49, v48
	v_fmac_f32_e32 v49, v50, v45
	v_fma_f32 v40, -v40, v49, v48
	v_div_fmas_f32 v40, v40, v45, v49
	v_div_fixup_f32 v46, v40, v46, v43
	v_lshlrev_b32_e32 v43, 16, v41
	v_and_b32_e32 v45, 0xffff0000, v41
	v_mul_f32_e32 v40, 0xbfb8aa3b, v43
	v_mul_f32_e32 v41, 0xbfb8aa3b, v45
	v_exp_f32_e32 v40, v40
	v_exp_f32_e32 v41, v41
	v_pk_mul_f32 v[34:35], v[34:35], v[46:47]
	v_pk_add_f32 v[40:41], v[40:41], 1.0 op_sel_hi:[1,0]
	s_nop 0
	v_div_scale_f32 v46, s[0:1], v41, v41, v45
	v_rcp_f32_e32 v47, v46
	v_cvt_pk_bf16_f32 v34, v34, v35
	v_fma_f32 v48, -v46, v47, 1.0
	v_fmac_f32_e32 v47, v48, v47
	v_div_scale_f32 v48, vcc, v45, v41, v45
	v_mul_f32_e32 v49, v48, v47
	v_fma_f32 v50, -v46, v49, v48
	v_fmac_f32_e32 v49, v50, v47
	v_fma_f32 v46, -v46, v49, v48
	v_div_fmas_f32 v46, v46, v47, v49
	v_div_fixup_f32 v41, v46, v41, v45
	v_div_scale_f32 v45, s[0:1], v40, v40, v43
	v_rcp_f32_e32 v46, v45
	s_nop 0
	v_fma_f32 v47, -v45, v46, 1.0
	v_fmac_f32_e32 v46, v47, v46
	v_div_scale_f32 v47, vcc, v43, v40, v43
	v_mul_f32_e32 v48, v47, v46
	v_fma_f32 v49, -v45, v48, v47
	v_fmac_f32_e32 v48, v49, v46
	v_fma_f32 v45, -v45, v48, v47
	v_div_fmas_f32 v45, v45, v46, v48
	v_div_fixup_f32 v40, v45, v40, v43
	v_pk_mul_f32 v[36:37], v[36:37], v[40:41]
	s_nop 0
	v_cvt_pk_bf16_f32 v35, v36, v37
	global_store_dwordx2 v[4:5], v[34:35], off
	v_or_b32_e32 v34, 32, v8
	v_lshlrev_b32_e32 v4, 1, v34
	v_mov_b32_e32 v5, v9
	v_lshl_add_u64 v[36:37], v[6:7], 0, v[4:5]
	s_waitcnt vmcnt(3)
	v_mov_b64_e32 v[36:37], v[180:181]
	v_lshl_add_u64 v[4:5], v[0:1], 0, v[4:5]
	v_mov_b32_e32 v35, v9
	s_nop 0
	v_lshlrev_b32_e32 v43, 16, v36
	v_and_b32_e32 v36, 0xffff0000, v36
	v_mul_f32_e32 v40, 0xbfb8aa3b, v43
	v_mul_f32_e32 v41, 0xbfb8aa3b, v36
	v_exp_f32_e32 v40, v40
	v_exp_f32_e32 v41, v41
	s_nop 0
	v_pk_add_f32 v[40:41], v[40:41], 1.0 op_sel_hi:[1,0]
	s_nop 0
	v_div_scale_f32 v45, s[0:1], v41, v41, v36
	v_rcp_f32_e32 v46, v45
	s_nop 0
	v_fma_f32 v47, -v45, v46, 1.0
	v_fmac_f32_e32 v46, v47, v46
	v_div_scale_f32 v47, vcc, v36, v41, v36
	v_mul_f32_e32 v48, v47, v46
	v_fma_f32 v49, -v45, v48, v47
	v_fmac_f32_e32 v48, v49, v46
	v_fma_f32 v45, -v45, v48, v47
	v_div_fmas_f32 v45, v45, v46, v48
	v_div_fixup_f32 v41, v45, v41, v36
	v_div_scale_f32 v36, s[0:1], v40, v40, v43
	v_rcp_f32_e32 v45, v36
	s_nop 0
	v_fma_f32 v46, -v36, v45, 1.0
	v_fmac_f32_e32 v45, v46, v45
	v_div_scale_f32 v46, vcc, v43, v40, v43
	v_mul_f32_e32 v47, v46, v45
	v_fma_f32 v48, -v36, v47, v46
	v_fmac_f32_e32 v47, v48, v45
	v_fma_f32 v36, -v36, v47, v46
	v_div_fmas_f32 v36, v36, v45, v47
	v_div_fixup_f32 v40, v36, v40, v43
	v_pk_mul_f32 v[30:31], v[30:31], v[40:41]
	v_lshlrev_b32_e32 v40, 16, v37
	v_and_b32_e32 v41, 0xffff0000, v37
	v_mul_f32_e32 v36, 0xbfb8aa3b, v40
	v_mul_f32_e32 v37, 0xbfb8aa3b, v41
	v_exp_f32_e32 v36, v36
	v_exp_f32_e32 v37, v37
	v_cvt_pk_bf16_f32 v30, v30, v31
	v_pk_add_f32 v[36:37], v[36:37], 1.0 op_sel_hi:[1,0]
	s_nop 0
	v_div_scale_f32 v43, s[0:1], v37, v37, v41
	v_rcp_f32_e32 v45, v43
	s_nop 0
	v_fma_f32 v46, -v43, v45, 1.0
	v_fmac_f32_e32 v45, v46, v45
	v_div_scale_f32 v46, vcc, v41, v37, v41
	v_mul_f32_e32 v47, v46, v45
	v_fma_f32 v48, -v43, v47, v46
	v_fmac_f32_e32 v47, v48, v45
	v_fma_f32 v43, -v43, v47, v46
	v_div_fmas_f32 v43, v43, v45, v47
	v_div_fixup_f32 v37, v43, v37, v41
	v_div_scale_f32 v41, s[0:1], v36, v36, v40
	v_rcp_f32_e32 v43, v41
	s_nop 0
	v_fma_f32 v45, -v41, v43, 1.0
	v_fmac_f32_e32 v43, v45, v43
	v_div_scale_f32 v45, vcc, v40, v36, v40
	v_mul_f32_e32 v46, v45, v43
	v_fma_f32 v47, -v41, v46, v45
	v_fmac_f32_e32 v46, v47, v43
	v_fma_f32 v41, -v41, v46, v45
	v_div_fmas_f32 v41, v41, v43, v46
	v_div_fixup_f32 v36, v41, v36, v40
	v_pk_mul_f32 v[32:33], v[32:33], v[36:37]
	s_nop 0
	v_cvt_pk_bf16_f32 v31, v32, v33
	global_store_dwordx2 v[4:5], v[30:31], off
	v_or_b32_e32 v4, 48, v8
	v_lshlrev_b32_e32 v30, 1, v4
	v_mov_b32_e32 v31, v9
	v_lshl_add_u64 v[6:7], v[6:7], 0, v[30:31]
	s_waitcnt vmcnt(3)
	v_mov_b64_e32 v[6:7], v[182:183]
	v_lshl_add_u64 v[0:1], v[0:1], 0, v[30:31]
	v_mov_b32_e32 v5, v9
	s_nop 0
	v_lshlrev_b32_e32 v36, 16, v6
	v_and_b32_e32 v6, 0xffff0000, v6
	v_mul_f32_e32 v32, 0xbfb8aa3b, v36
	v_mul_f32_e32 v33, 0xbfb8aa3b, v6
	v_exp_f32_e32 v32, v32
	v_exp_f32_e32 v33, v33
	s_nop 0
	v_pk_add_f32 v[32:33], v[32:33], 1.0 op_sel_hi:[1,0]
	s_nop 0
	v_div_scale_f32 v37, s[0:1], v33, v33, v6
	v_rcp_f32_e32 v40, v37
	s_nop 0
	v_fma_f32 v41, -v37, v40, 1.0
	v_fmac_f32_e32 v40, v41, v40
	v_div_scale_f32 v41, vcc, v6, v33, v6
	v_mul_f32_e32 v43, v41, v40
	v_fma_f32 v45, -v37, v43, v41
	v_fmac_f32_e32 v43, v45, v40
	v_fma_f32 v37, -v37, v43, v41
	v_div_fmas_f32 v37, v37, v40, v43
	v_div_fixup_f32 v33, v37, v33, v6
	v_div_scale_f32 v6, s[0:1], v32, v32, v36
	v_rcp_f32_e32 v37, v6
	s_nop 0
	v_fma_f32 v40, -v6, v37, 1.0
	v_fmac_f32_e32 v37, v40, v37
	v_div_scale_f32 v40, vcc, v36, v32, v36
	v_mul_f32_e32 v41, v40, v37
	v_fma_f32 v43, -v6, v41, v40
	v_fmac_f32_e32 v41, v43, v37
	v_fma_f32 v6, -v6, v41, v40
	v_div_fmas_f32 v6, v6, v37, v41
	v_div_fixup_f32 v32, v6, v32, v36
	v_pk_mul_f32 v[26:27], v[26:27], v[32:33]
	v_lshlrev_b32_e32 v32, 16, v7
	v_and_b32_e32 v33, 0xffff0000, v7
	v_mul_f32_e32 v6, 0xbfb8aa3b, v32
	v_mul_f32_e32 v2, 0xbfb8aa3b, v33
	v_exp_f32_e32 v6, v6
	v_exp_f32_e32 v7, v2
	v_cvt_pk_bf16_f32 v26, v26, v27
	v_pk_add_f32 v[6:7], v[6:7], 1.0 op_sel_hi:[1,0]
	s_nop 0
	v_div_scale_f32 v2, s[0:1], v7, v7, v33
	v_rcp_f32_e32 v36, v2
	s_nop 0
	v_fma_f32 v37, -v2, v36, 1.0
	v_fmac_f32_e32 v36, v37, v36
	v_div_scale_f32 v37, vcc, v33, v7, v33
	v_mul_f32_e32 v40, v37, v36
	v_fma_f32 v41, -v2, v40, v37
	v_fmac_f32_e32 v40, v41, v36
	v_fma_f32 v2, -v2, v40, v37
	v_div_fmas_f32 v2, v2, v36, v40
	v_div_fixup_f32 v7, v2, v7, v33
	v_div_scale_f32 v2, s[0:1], v6, v6, v32
	v_rcp_f32_e32 v33, v2
	s_nop 0
	v_fma_f32 v36, -v2, v33, 1.0
	v_fmac_f32_e32 v33, v36, v33
	v_div_scale_f32 v36, vcc, v32, v6, v32
	v_mul_f32_e32 v37, v36, v33
	v_fma_f32 v40, -v2, v37, v36
	v_fmac_f32_e32 v37, v40, v33
	v_fma_f32 v2, -v2, v37, v36
	v_div_fmas_f32 v2, v2, v33, v37
	v_div_fixup_f32 v6, v2, v6, v32
	v_pk_mul_f32 v[6:7], v[28:29], v[6:7]
	v_mov_b64_e32 v[36:37], v[8:9]
	v_cvt_pk_bf16_f32 v27, v6, v7
	global_store_dwordx2 v[0:1], v[26:27], off
	ds_bpermute_b32 v0, v44, v139
	s_waitcnt lgkmcnt(0)
	v_add_f32_e32 v0, v139, v0
	ds_bpermute_b32 v1, v3, v0
.LBB0_202:
	s_waitcnt lgkmcnt(0)
	v_add_f32_e32 v0, v0, v1
	v_div_scale_f32 v1, s[0:1], v0, v0, 1.0
	v_rcp_f32_e32 v2, v1
	v_readlane_b32 s0, v251, 10
	v_readlane_b32 s2, v251, 12
	v_readlane_b32 s3, v251, 13
	v_fma_f32 v3, -v1, v2, 1.0
	v_fmac_f32_e32 v2, v3, v2
	v_div_scale_f32 v3, vcc, 1.0, v0, 1.0
	v_mul_f32_e32 v6, v3, v2
	v_fma_f32 v7, -v1, v6, v3
	v_fmac_f32_e32 v6, v7, v2
	v_fma_f32 v1, -v1, v6, v3
	v_div_fmas_f32 v1, v1, v2, v6
	v_div_fixup_f32 v2, v1, v0, 1.0
	v_or_b32_e32 v3, 16, v42
	v_readlane_b32 s1, v251, 11
	v_mov_b64_e32 v[0:1], s[2:3]
	v_mad_i64_i32 v[0:1], s[0:1], v3, s77, v[0:1]
	s_mov_b64 s[0:1], 0x4f01000
	s_nop 0
	v_lshl_add_u64 v[6:7], v[0:1], 0, s[0:1]
	v_lshlrev_b64 v[26:27], 1, v[36:37]
	v_lshl_add_u64 v[28:29], v[6:7], 0, v[26:27]
	v_mov_b64_e32 v[176:177], v[28:29]
	global_load_dwordx2 v[28:29], v[28:29], off
	global_load_dwordx2 v[178:179], v[176:177], off offset:32
	global_load_dwordx2 v[180:181], v[176:177], off offset:64
	global_load_dwordx2 v[182:183], v[176:177], off offset:96
	s_movk_i32 s0, 0xec00
	v_mad_i64_i32 v[0:1], s[0:1], v3, s0, v[0:1]
	s_mov_b64 s[0:1], 0xb00200
	s_nop 0
	v_lshl_add_u64 v[0:1], v[0:1], 0, s[0:1]
	v_lshlrev_b64 v[4:5], 1, v[4:5]
	s_waitcnt vmcnt(3)
	v_lshlrev_b32_e32 v3, 16, v28
	v_and_b32_e32 v8, 0xffff0000, v28
	v_mul_f32_e32 v28, 0xbfb8aa3b, v3
	v_exp_f32_e32 v30, v28
	v_mul_f32_e32 v28, 0xbfb8aa3b, v8
	v_exp_f32_e32 v31, v28
	v_pk_mul_f32 v[22:23], v[2:3], v[22:23] op_sel_hi:[0,1]
	v_pk_add_f32 v[30:31], v[30:31], 1.0 op_sel_hi:[1,0]
	s_nop 0
	v_div_scale_f32 v28, s[0:1], v31, v31, v8
	v_rcp_f32_e32 v32, v28
	s_nop 0
	v_fma_f32 v33, -v28, v32, 1.0
	v_fmac_f32_e32 v32, v33, v32
	v_div_scale_f32 v33, vcc, v8, v31, v8
	v_mul_f32_e32 v36, v33, v32
	v_fma_f32 v37, -v28, v36, v33
	v_fmac_f32_e32 v36, v37, v32
	v_fma_f32 v28, -v28, v36, v33
	v_div_fmas_f32 v28, v28, v32, v36
	v_div_fixup_f32 v31, v28, v31, v8
	v_div_scale_f32 v8, s[0:1], v30, v30, v3
	v_rcp_f32_e32 v28, v8
	s_nop 0
	v_fma_f32 v32, -v8, v28, 1.0
	v_fmac_f32_e32 v28, v32, v28
	v_div_scale_f32 v32, vcc, v3, v30, v3
	v_mul_f32_e32 v33, v32, v28
	v_fma_f32 v36, -v8, v33, v32
	v_fmac_f32_e32 v33, v36, v28
	v_fma_f32 v8, -v8, v33, v32
	v_div_fmas_f32 v8, v8, v28, v33
	v_div_fixup_f32 v30, v8, v30, v3
	v_lshlrev_b32_e32 v3, 16, v29
	v_and_b32_e32 v8, 0xffff0000, v29
	v_mul_f32_e32 v28, 0xbfb8aa3b, v3
	v_mul_f32_e32 v29, 0xbfb8aa3b, v8
	v_exp_f32_e32 v28, v28
	v_exp_f32_e32 v29, v29
	v_pk_mul_f32 v[22:23], v[22:23], v[30:31]
	v_pk_mul_f32 v[24:25], v[2:3], v[24:25] op_sel_hi:[0,1]
	v_cvt_pk_bf16_f32 v22, v22, v23
	v_pk_add_f32 v[28:29], v[28:29], 1.0 op_sel_hi:[1,0]
	s_nop 0
	v_div_scale_f32 v30, s[0:1], v29, v29, v8
	v_rcp_f32_e32 v31, v30
	s_nop 0
	v_fma_f32 v32, -v30, v31, 1.0
	v_fmac_f32_e32 v31, v32, v31
	v_div_scale_f32 v32, vcc, v8, v29, v8
	v_mul_f32_e32 v33, v32, v31
	v_fma_f32 v36, -v30, v33, v32
	v_fmac_f32_e32 v33, v36, v31
	v_fma_f32 v30, -v30, v33, v32
	v_div_fmas_f32 v30, v30, v31, v33
	v_div_fixup_f32 v29, v30, v29, v8
	v_div_scale_f32 v8, s[0:1], v28, v28, v3
	v_rcp_f32_e32 v30, v8
	s_nop 0
	v_fma_f32 v31, -v8, v30, 1.0
	v_fmac_f32_e32 v30, v31, v30
	v_div_scale_f32 v31, vcc, v3, v28, v3
	v_mul_f32_e32 v32, v31, v30
	v_fma_f32 v33, -v8, v32, v31
	v_fmac_f32_e32 v32, v33, v30
	v_fma_f32 v8, -v8, v32, v31
	v_div_fmas_f32 v8, v8, v30, v32
	v_div_fixup_f32 v28, v8, v28, v3
	v_pk_mul_f32 v[24:25], v[24:25], v[28:29]
	s_nop 0
	v_cvt_pk_bf16_f32 v23, v24, v25
	v_lshl_add_u64 v[24:25], v[0:1], 0, v[26:27]
	global_store_dwordx2 v[24:25], v[22:23], off
	v_lshlrev_b64 v[22:23], 1, v[38:39]
	v_lshl_add_u64 v[24:25], v[6:7], 0, v[22:23]
	s_waitcnt vmcnt(3)
	v_mov_b64_e32 v[24:25], v[178:179]
	s_nop 0
	v_lshlrev_b32_e32 v3, 16, v24
	v_and_b32_e32 v8, 0xffff0000, v24
	v_mul_f32_e32 v24, 0xbfb8aa3b, v3
	v_exp_f32_e32 v26, v24
	v_mul_f32_e32 v24, 0xbfb8aa3b, v8
	v_exp_f32_e32 v27, v24
	v_pk_mul_f32 v[18:19], v[2:3], v[18:19] op_sel_hi:[0,1]
	v_pk_add_f32 v[26:27], v[26:27], 1.0 op_sel_hi:[1,0]
	s_nop 0
	v_div_scale_f32 v24, s[0:1], v27, v27, v8
	v_rcp_f32_e32 v28, v24
	s_nop 0
	v_fma_f32 v29, -v24, v28, 1.0
	v_fmac_f32_e32 v28, v29, v28
	v_div_scale_f32 v29, vcc, v8, v27, v8
	v_mul_f32_e32 v30, v29, v28
	v_fma_f32 v31, -v24, v30, v29
	v_fmac_f32_e32 v30, v31, v28
	v_fma_f32 v24, -v24, v30, v29
	v_div_fmas_f32 v24, v24, v28, v30
	v_div_fixup_f32 v27, v24, v27, v8
	v_div_scale_f32 v8, s[0:1], v26, v26, v3
	v_rcp_f32_e32 v24, v8
	s_nop 0
	v_fma_f32 v28, -v8, v24, 1.0
	v_fmac_f32_e32 v24, v28, v24
	v_div_scale_f32 v28, vcc, v3, v26, v3
	v_mul_f32_e32 v29, v28, v24
	v_fma_f32 v30, -v8, v29, v28
	v_fmac_f32_e32 v29, v30, v24
	v_fma_f32 v8, -v8, v29, v28
	v_div_fmas_f32 v8, v8, v24, v29
	v_div_fixup_f32 v26, v8, v26, v3
	v_lshlrev_b32_e32 v3, 16, v25
	v_and_b32_e32 v8, 0xffff0000, v25
	v_mul_f32_e32 v24, 0xbfb8aa3b, v3
	v_mul_f32_e32 v25, 0xbfb8aa3b, v8
	v_exp_f32_e32 v24, v24
	v_exp_f32_e32 v25, v25
	v_pk_mul_f32 v[18:19], v[18:19], v[26:27]
	v_pk_mul_f32 v[20:21], v[2:3], v[20:21] op_sel_hi:[0,1]
	v_cvt_pk_bf16_f32 v18, v18, v19
	v_pk_add_f32 v[24:25], v[24:25], 1.0 op_sel_hi:[1,0]
	s_nop 0
	v_div_scale_f32 v26, s[0:1], v25, v25, v8
	v_rcp_f32_e32 v27, v26
	s_nop 0
	v_fma_f32 v28, -v26, v27, 1.0
	v_fmac_f32_e32 v27, v28, v27
	v_div_scale_f32 v28, vcc, v8, v25, v8
	v_mul_f32_e32 v29, v28, v27
	v_fma_f32 v30, -v26, v29, v28
	v_fmac_f32_e32 v29, v30, v27
	v_fma_f32 v26, -v26, v29, v28
	v_div_fmas_f32 v26, v26, v27, v29
	v_div_fixup_f32 v25, v26, v25, v8
	v_div_scale_f32 v8, s[0:1], v24, v24, v3
	v_rcp_f32_e32 v26, v8
	s_nop 0
	v_fma_f32 v27, -v8, v26, 1.0
	v_fmac_f32_e32 v26, v27, v26
	v_div_scale_f32 v27, vcc, v3, v24, v3
	v_mul_f32_e32 v28, v27, v26
	v_fma_f32 v29, -v8, v28, v27
	v_fmac_f32_e32 v28, v29, v26
	v_fma_f32 v8, -v8, v28, v27
	v_div_fmas_f32 v8, v8, v26, v28
	v_div_fixup_f32 v24, v8, v24, v3
	v_pk_mul_f32 v[20:21], v[20:21], v[24:25]
	s_nop 0
	v_cvt_pk_bf16_f32 v19, v20, v21
	v_lshl_add_u64 v[20:21], v[0:1], 0, v[22:23]
	global_store_dwordx2 v[20:21], v[18:19], off
	v_lshlrev_b64 v[18:19], 1, v[34:35]
	v_lshl_add_u64 v[20:21], v[6:7], 0, v[18:19]
	s_waitcnt vmcnt(3)
	v_mov_b64_e32 v[20:21], v[180:181]
	v_lshl_add_u64 v[6:7], v[6:7], 0, v[4:5]
	s_nop 0
	v_lshlrev_b32_e32 v3, 16, v20
	v_and_b32_e32 v8, 0xffff0000, v20
	v_mul_f32_e32 v20, 0xbfb8aa3b, v3
	v_exp_f32_e32 v22, v20
	v_mul_f32_e32 v20, 0xbfb8aa3b, v8
	v_exp_f32_e32 v23, v20
	v_pk_mul_f32 v[14:15], v[2:3], v[14:15] op_sel_hi:[0,1]
	v_pk_add_f32 v[22:23], v[22:23], 1.0 op_sel_hi:[1,0]
	s_nop 0
	v_div_scale_f32 v20, s[0:1], v23, v23, v8
	v_rcp_f32_e32 v24, v20
	s_nop 0
	v_fma_f32 v25, -v20, v24, 1.0
	v_fmac_f32_e32 v24, v25, v24
	v_div_scale_f32 v25, vcc, v8, v23, v8
	v_mul_f32_e32 v26, v25, v24
	v_fma_f32 v27, -v20, v26, v25
	v_fmac_f32_e32 v26, v27, v24
	v_fma_f32 v20, -v20, v26, v25
	v_div_fmas_f32 v20, v20, v24, v26
	v_div_fixup_f32 v23, v20, v23, v8
	v_div_scale_f32 v8, s[0:1], v22, v22, v3
	v_rcp_f32_e32 v20, v8
	s_nop 0
	v_fma_f32 v24, -v8, v20, 1.0
	v_fmac_f32_e32 v20, v24, v20
	v_div_scale_f32 v24, vcc, v3, v22, v3
	v_mul_f32_e32 v25, v24, v20
	v_fma_f32 v26, -v8, v25, v24
	v_fmac_f32_e32 v25, v26, v20
	v_fma_f32 v8, -v8, v25, v24
	v_div_fmas_f32 v8, v8, v20, v25
	v_div_fixup_f32 v22, v8, v22, v3
	v_lshlrev_b32_e32 v3, 16, v21
	v_and_b32_e32 v8, 0xffff0000, v21
	v_mul_f32_e32 v20, 0xbfb8aa3b, v3
	v_mul_f32_e32 v21, 0xbfb8aa3b, v8
	v_exp_f32_e32 v20, v20
	v_exp_f32_e32 v21, v21
	v_pk_mul_f32 v[14:15], v[14:15], v[22:23]
	v_pk_mul_f32 v[16:17], v[2:3], v[16:17] op_sel_hi:[0,1]
	v_cvt_pk_bf16_f32 v14, v14, v15
	v_pk_add_f32 v[20:21], v[20:21], 1.0 op_sel_hi:[1,0]
	s_nop 0
	v_div_scale_f32 v22, s[0:1], v21, v21, v8
	v_rcp_f32_e32 v23, v22
	s_nop 0
	v_fma_f32 v24, -v22, v23, 1.0
	v_fmac_f32_e32 v23, v24, v23
	v_div_scale_f32 v24, vcc, v8, v21, v8
	v_mul_f32_e32 v25, v24, v23
	v_fma_f32 v26, -v22, v25, v24
	v_fmac_f32_e32 v25, v26, v23
	v_fma_f32 v22, -v22, v25, v24
	v_div_fmas_f32 v22, v22, v23, v25
	v_div_fixup_f32 v21, v22, v21, v8
	v_div_scale_f32 v8, s[0:1], v20, v20, v3
	v_rcp_f32_e32 v22, v8
	s_nop 0
	v_fma_f32 v23, -v8, v22, 1.0
	v_fmac_f32_e32 v22, v23, v22
	v_div_scale_f32 v23, vcc, v3, v20, v3
	v_mul_f32_e32 v24, v23, v22
	v_fma_f32 v25, -v8, v24, v23
	v_fmac_f32_e32 v24, v25, v22
	v_fma_f32 v8, -v8, v24, v23
	v_div_fmas_f32 v8, v8, v22, v24
	v_div_fixup_f32 v20, v8, v20, v3
	v_pk_mul_f32 v[16:17], v[16:17], v[20:21]
	s_nop 0
	v_cvt_pk_bf16_f32 v15, v16, v17
	v_lshl_add_u64 v[16:17], v[0:1], 0, v[18:19]
	global_store_dwordx2 v[16:17], v[14:15], off
	s_waitcnt vmcnt(3)
	v_mov_b64_e32 v[14:15], v[182:183]
	v_lshl_add_u64 v[0:1], v[0:1], 0, v[4:5]
	s_nop 0
	v_lshlrev_b32_e32 v3, 16, v14
	v_and_b32_e32 v8, 0xffff0000, v14
	v_mul_f32_e32 v6, 0xbfb8aa3b, v3
	v_mul_f32_e32 v7, 0xbfb8aa3b, v8
	v_exp_f32_e32 v6, v6
	v_exp_f32_e32 v7, v7
	v_pk_mul_f32 v[10:11], v[2:3], v[10:11] op_sel_hi:[0,1]
	v_pk_add_f32 v[6:7], v[6:7], 1.0 op_sel_hi:[1,0]
	s_nop 0
	v_div_scale_f32 v14, s[0:1], v7, v7, v8
	v_rcp_f32_e32 v16, v14
	s_nop 0
	v_fma_f32 v17, -v14, v16, 1.0
	v_fmac_f32_e32 v16, v17, v16
	v_div_scale_f32 v17, vcc, v8, v7, v8
	v_mul_f32_e32 v18, v17, v16
	v_fma_f32 v19, -v14, v18, v17
	v_fmac_f32_e32 v18, v19, v16
	v_fma_f32 v14, -v14, v18, v17
	v_div_fmas_f32 v14, v14, v16, v18
	v_div_fixup_f32 v7, v14, v7, v8
	v_div_scale_f32 v8, s[0:1], v6, v6, v3
	v_rcp_f32_e32 v14, v8
	s_nop 0
	v_fma_f32 v16, -v8, v14, 1.0
	v_fmac_f32_e32 v14, v16, v14
	v_div_scale_f32 v16, vcc, v3, v6, v3
	v_mul_f32_e32 v17, v16, v14
	v_fma_f32 v18, -v8, v17, v16
	v_fmac_f32_e32 v17, v18, v14
	v_fma_f32 v8, -v8, v17, v16
	v_div_fmas_f32 v8, v8, v14, v17
	v_div_fixup_f32 v6, v8, v6, v3
	v_lshlrev_b32_e32 v8, 16, v15
	v_and_b32_e32 v14, 0xffff0000, v15
	v_pk_mul_f32 v[6:7], v[10:11], v[6:7]
	v_mul_f32_e32 v3, 0xbfb8aa3b, v8
	v_mul_f32_e32 v11, 0xbfb8aa3b, v14
	v_exp_f32_e32 v10, v3
	v_exp_f32_e32 v11, v11
	v_pk_mul_f32 v[2:3], v[2:3], v[12:13] op_sel_hi:[0,1]
	v_cvt_pk_bf16_f32 v6, v6, v7
	v_pk_add_f32 v[10:11], v[10:11], 1.0 op_sel_hi:[1,0]
	s_nop 0
	v_div_scale_f32 v12, s[0:1], v11, v11, v14
	v_rcp_f32_e32 v13, v12
	s_nop 0
	v_fma_f32 v15, -v12, v13, 1.0
	v_fmac_f32_e32 v13, v15, v13
	v_div_scale_f32 v15, vcc, v14, v11, v14
	v_mul_f32_e32 v16, v15, v13
	v_fma_f32 v17, -v12, v16, v15
	v_fmac_f32_e32 v16, v17, v13
	v_fma_f32 v12, -v12, v16, v15
	v_div_fmas_f32 v12, v12, v13, v16
	v_div_fixup_f32 v11, v12, v11, v14
	v_div_scale_f32 v12, s[0:1], v10, v10, v8
	v_rcp_f32_e32 v13, v12
	s_nop 0
	v_fma_f32 v14, -v12, v13, 1.0
	v_fmac_f32_e32 v13, v14, v13
	v_div_scale_f32 v14, vcc, v8, v10, v8
	v_mul_f32_e32 v15, v14, v13
	v_fma_f32 v16, -v12, v15, v14
	v_fmac_f32_e32 v15, v16, v13
	v_fma_f32 v12, -v12, v15, v14
	v_div_fmas_f32 v12, v12, v13, v15
	v_div_fixup_f32 v10, v12, v10, v8
	v_pk_mul_f32 v[2:3], v[2:3], v[10:11]
	s_nop 0
	v_cvt_pk_bf16_f32 v7, v2, v3
	global_store_dwordx2 v[0:1], v[6:7], off

.LBB0_228:
	s_waitcnt vmcnt(0)
	v_and_b32_e32 v35, 64, v220
	v_xor_b32_e32 v34, 16, v220
	v_add_u32_e32 v35, 64, v35
	v_cmp_lt_i32_e32 vcc, v34, v35
	v_or_b32_e32 v42, s2, v165
	v_lshl_or_b32 v36, v166, 2, s3
	v_cndmask_b32_e32 v34, v220, v34, vcc
	v_lshlrev_b32_e32 v48, 2, v34
	v_xor_b32_e32 v34, 32, v220
	v_cmp_lt_i32_e32 vcc, v34, v35
	v_ashrrev_i32_e32 v43, 31, v42
	v_mov_b32_e32 v37, v9
	v_cndmask_b32_e32 v34, v220, v34, vcc
	v_lshlrev_b32_e32 v45, 2, v34
	ds_bpermute_b32 v34, v48, v134
	s_waitcnt lgkmcnt(0)
	v_add_f32_e32 v34, v134, v34
	ds_bpermute_b32 v35, v45, v34
	s_waitcnt lgkmcnt(0)
	v_add_f32_e32 v34, v34, v35
	v_div_scale_f32 v35, s[0:1], v34, v34, 1.0
	v_rcp_f32_e32 v38, v35
	s_nop 0
	v_fma_f32 v39, -v35, v38, 1.0
	v_fmac_f32_e32 v38, v39, v38
	v_div_scale_f32 v39, vcc, 1.0, v34, 1.0
	v_mul_f32_e32 v40, v39, v38
	v_fma_f32 v41, -v35, v40, v39
	v_fmac_f32_e32 v40, v41, v38
	v_fma_f32 v35, -v35, v40, v39
	v_div_fmas_f32 v35, v35, v38, v40
	v_div_fixup_f32 v44, v35, v34, 1.0
	v_mov_b64_e32 v[34:35], s[70:71]
	v_mad_i64_i32 v[34:35], s[0:1], v42, s77, v[34:35]
	s_mov_b64 s[0:1], 0x1000
	s_nop 0
	v_lshl_add_u64 v[46:47], v[34:35], 0, s[0:1]
	v_readlane_b32 s0, v251, 10
	v_lshlrev_b64 v[34:35], 11, v[42:43]
	v_readlane_b32 s1, v251, 11
	v_readlane_b32 s2, v251, 12
	v_readlane_b32 s3, v251, 13
	s_mov_b64 s[0:1], 0xb00200
	v_pk_mul_f32 v[30:31], v[30:31], v[44:45] op_sel_hi:[1,0]
	v_lshl_add_u64 v[34:35], s[2:3], 0, v[34:35]
	v_lshl_add_u64 v[40:41], v[34:35], 0, s[0:1]
	v_lshlrev_b32_e32 v34, 1, v36
	v_mov_b32_e32 v35, v9
	v_lshl_add_u64 v[38:39], v[46:47], 0, v[34:35]
	v_mov_b64_e32 v[176:177], v[38:39]
	global_load_dwordx2 v[38:39], v[38:39], off
	global_load_dwordx2 v[178:179], v[176:177], off offset:32
	global_load_dwordx2 v[180:181], v[176:177], off offset:64
	global_load_dwordx2 v[182:183], v[176:177], off offset:96
	v_pk_mul_f32 v[32:33], v[32:33], v[44:45] op_sel_hi:[1,0]
	v_pk_mul_f32 v[26:27], v[26:27], v[44:45] op_sel_hi:[1,0]
	v_pk_mul_f32 v[28:29], v[28:29], v[44:45] op_sel_hi:[1,0]
	v_pk_mul_f32 v[4:5], v[4:5], v[44:45] op_sel_hi:[1,0]
	v_pk_mul_f32 v[6:7], v[6:7], v[44:45] op_sel_hi:[1,0]
	v_pk_mul_f32 v[0:1], v[0:1], v[44:45] op_sel_hi:[1,0]
	v_pk_mul_f32 v[2:3], v[2:3], v[44:45] op_sel_hi:[1,0]
	s_waitcnt vmcnt(3)
	v_lshlrev_b32_e32 v43, 16, v38
	v_and_b32_e32 v38, 0xffff0000, v38
	v_mul_f32_e32 v49, 0xbfb8aa3b, v43
	v_exp_f32_e32 v50, v49
	v_mul_f32_e32 v49, 0xbfb8aa3b, v38
	v_exp_f32_e32 v51, v49
	s_nop 0
	v_pk_add_f32 v[50:51], v[50:51], 1.0 op_sel_hi:[1,0]
	s_nop 0
	v_div_scale_f32 v49, s[0:1], v51, v51, v38
	v_rcp_f32_e32 v52, v49
	s_nop 0
	v_fma_f32 v53, -v49, v52, 1.0
	v_fmac_f32_e32 v52, v53, v52
	v_div_scale_f32 v53, vcc, v38, v51, v38
	v_mul_f32_e32 v54, v53, v52
	v_fma_f32 v55, -v49, v54, v53
	v_fmac_f32_e32 v54, v55, v52
	v_fma_f32 v49, -v49, v54, v53
	v_div_fmas_f32 v49, v49, v52, v54
	v_div_fixup_f32 v51, v49, v51, v38
	v_div_scale_f32 v38, s[0:1], v50, v50, v43
	v_rcp_f32_e32 v49, v38
	s_nop 0
	v_fma_f32 v52, -v38, v49, 1.0
	v_fmac_f32_e32 v49, v52, v49
	v_div_scale_f32 v52, vcc, v43, v50, v43
	v_mul_f32_e32 v53, v52, v49
	v_fma_f32 v54, -v38, v53, v52
	v_fmac_f32_e32 v53, v54, v49
	v_fma_f32 v38, -v38, v53, v52
	v_div_fmas_f32 v38, v38, v49, v53
	v_div_fixup_f32 v50, v38, v50, v43
	v_lshlrev_b32_e32 v43, 16, v39
	v_and_b32_e32 v49, 0xffff0000, v39
	v_mul_f32_e32 v38, 0xbfb8aa3b, v43
	v_mul_f32_e32 v39, 0xbfb8aa3b, v49
	v_exp_f32_e32 v38, v38
	v_exp_f32_e32 v39, v39
	v_pk_mul_f32 v[30:31], v[30:31], v[50:51]
	v_pk_add_f32 v[38:39], v[38:39], 1.0 op_sel_hi:[1,0]
	s_nop 0
	v_div_scale_f32 v50, s[0:1], v39, v39, v49
	v_rcp_f32_e32 v51, v50
	v_cvt_pk_bf16_f32 v30, v30, v31
	v_fma_f32 v52, -v50, v51, 1.0
	v_fmac_f32_e32 v51, v52, v51
	v_div_scale_f32 v52, vcc, v49, v39, v49
	v_mul_f32_e32 v53, v52, v51
	v_fma_f32 v54, -v50, v53, v52
	v_fmac_f32_e32 v53, v54, v51
	v_fma_f32 v50, -v50, v53, v52
	v_div_fmas_f32 v50, v50, v51, v53
	v_div_fixup_f32 v39, v50, v39, v49
	v_div_scale_f32 v49, s[0:1], v38, v38, v43
	v_rcp_f32_e32 v50, v49
	s_nop 0
	v_fma_f32 v51, -v49, v50, 1.0
	v_fmac_f32_e32 v50, v51, v50
	v_div_scale_f32 v51, vcc, v43, v38, v43
	v_mul_f32_e32 v52, v51, v50
	v_fma_f32 v53, -v49, v52, v51
	v_fmac_f32_e32 v52, v53, v50
	v_fma_f32 v49, -v49, v52, v51
	v_div_fmas_f32 v49, v49, v50, v52
	v_div_fixup_f32 v38, v49, v38, v43
	v_pk_mul_f32 v[32:33], v[32:33], v[38:39]
	v_or_b32_e32 v38, 16, v36
	v_cvt_pk_bf16_f32 v31, v32, v33
	v_lshl_add_u64 v[32:33], v[40:41], 0, v[34:35]
	global_store_dwordx2 v[32:33], v[30:31], off
	v_lshlrev_b32_e32 v30, 1, v38
	v_mov_b32_e32 v31, v9
	v_lshl_add_u64 v[32:33], v[46:47], 0, v[30:31]
	s_waitcnt vmcnt(3)
	v_mov_b64_e32 v[32:33], v[178:179]
	v_mov_b32_e32 v39, v9
	s_nop 0
	v_lshlrev_b32_e32 v43, 16, v32
	v_and_b32_e32 v32, 0xffff0000, v32
	v_mul_f32_e32 v34, 0xbfb8aa3b, v43
	v_mul_f32_e32 v35, 0xbfb8aa3b, v32
	v_exp_f32_e32 v34, v34
	v_exp_f32_e32 v35, v35
	s_nop 0
	v_pk_add_f32 v[34:35], v[34:35], 1.0 op_sel_hi:[1,0]
	s_nop 0
	v_div_scale_f32 v49, s[0:1], v35, v35, v32
	v_rcp_f32_e32 v50, v49
	s_nop 0
	v_fma_f32 v51, -v49, v50, 1.0
	v_fmac_f32_e32 v50, v51, v50
	v_div_scale_f32 v51, vcc, v32, v35, v32
	v_mul_f32_e32 v52, v51, v50
	v_fma_f32 v53, -v49, v52, v51
	v_fmac_f32_e32 v52, v53, v50
	v_fma_f32 v49, -v49, v52, v51
	v_div_fmas_f32 v49, v49, v50, v52
	v_div_fixup_f32 v35, v49, v35, v32
	v_div_scale_f32 v32, s[0:1], v34, v34, v43
	v_rcp_f32_e32 v49, v32
	s_nop 0
	v_fma_f32 v50, -v32, v49, 1.0
	v_fmac_f32_e32 v49, v50, v49
	v_div_scale_f32 v50, vcc, v43, v34, v43
	v_mul_f32_e32 v51, v50, v49
	v_fma_f32 v52, -v32, v51, v50
	v_fmac_f32_e32 v51, v52, v49
	v_fma_f32 v32, -v32, v51, v50
	v_div_fmas_f32 v32, v32, v49, v51
	v_div_fixup_f32 v34, v32, v34, v43
	v_pk_mul_f32 v[26:27], v[26:27], v[34:35]
	v_lshlrev_b32_e32 v34, 16, v33
	v_and_b32_e32 v35, 0xffff0000, v33
	v_mul_f32_e32 v32, 0xbfb8aa3b, v34
	v_mul_f32_e32 v33, 0xbfb8aa3b, v35
	v_exp_f32_e32 v32, v32
	v_exp_f32_e32 v33, v33
	v_cvt_pk_bf16_f32 v26, v26, v27
	v_pk_add_f32 v[32:33], v[32:33], 1.0 op_sel_hi:[1,0]
	s_nop 0
	v_div_scale_f32 v43, s[0:1], v33, v33, v35
	v_rcp_f32_e32 v49, v43
	s_nop 0
	v_fma_f32 v50, -v43, v49, 1.0
	v_fmac_f32_e32 v49, v50, v49
	v_div_scale_f32 v50, vcc, v35, v33, v35
	v_mul_f32_e32 v51, v50, v49
	v_fma_f32 v52, -v43, v51, v50
	v_fmac_f32_e32 v51, v52, v49
	v_fma_f32 v43, -v43, v51, v50
	v_div_fmas_f32 v43, v43, v49, v51
	v_div_fixup_f32 v33, v43, v33, v35
	v_div_scale_f32 v35, s[0:1], v32, v32, v34
	v_rcp_f32_e32 v43, v35
	s_nop 0
	v_fma_f32 v49, -v35, v43, 1.0
	v_fmac_f32_e32 v43, v49, v43
	v_div_scale_f32 v49, vcc, v34, v32, v34
	v_mul_f32_e32 v50, v49, v43
	v_fma_f32 v51, -v35, v50, v49
	v_fmac_f32_e32 v50, v51, v43
	v_fma_f32 v35, -v35, v50, v49
	v_div_fmas_f32 v35, v35, v43, v50
	v_div_fixup_f32 v32, v35, v32, v34
	v_pk_mul_f32 v[28:29], v[28:29], v[32:33]
	v_or_b32_e32 v34, 32, v36
	v_cvt_pk_bf16_f32 v27, v28, v29
	v_lshl_add_u64 v[28:29], v[40:41], 0, v[30:31]
	global_store_dwordx2 v[28:29], v[26:27], off
	v_lshlrev_b32_e32 v26, 1, v34
	v_mov_b32_e32 v27, v9
	v_lshl_add_u64 v[28:29], v[46:47], 0, v[26:27]
	s_waitcnt vmcnt(3)
	v_mov_b64_e32 v[28:29], v[180:181]
	v_mov_b32_e32 v35, v9
	s_nop 0
	v_lshlrev_b32_e32 v32, 16, v28
	v_and_b32_e32 v28, 0xffff0000, v28
	v_mul_f32_e32 v30, 0xbfb8aa3b, v32
	v_mul_f32_e32 v31, 0xbfb8aa3b, v28
	v_exp_f32_e32 v30, v30
	v_exp_f32_e32 v31, v31
	s_nop 0
	v_pk_add_f32 v[30:31], v[30:31], 1.0 op_sel_hi:[1,0]
	s_nop 0
	v_div_scale_f32 v33, s[0:1], v31, v31, v28
	v_rcp_f32_e32 v43, v33
	s_nop 0
	v_fma_f32 v49, -v33, v43, 1.0
	v_fmac_f32_e32 v43, v49, v43
	v_div_scale_f32 v49, vcc, v28, v31, v28
	v_mul_f32_e32 v50, v49, v43
	v_fma_f32 v51, -v33, v50, v49
	v_fmac_f32_e32 v50, v51, v43
	v_fma_f32 v33, -v33, v50, v49
	v_div_fmas_f32 v33, v33, v43, v50
	v_div_fixup_f32 v31, v33, v31, v28
	v_div_scale_f32 v28, s[0:1], v30, v30, v32
	v_rcp_f32_e32 v33, v28
	s_nop 0
	v_fma_f32 v43, -v28, v33, 1.0
	v_fmac_f32_e32 v33, v43, v33
	v_div_scale_f32 v43, vcc, v32, v30, v32
	v_mul_f32_e32 v49, v43, v33
	v_fma_f32 v50, -v28, v49, v43
	v_fmac_f32_e32 v49, v50, v33
	v_fma_f32 v28, -v28, v49, v43
	v_div_fmas_f32 v28, v28, v33, v49
	v_div_fixup_f32 v30, v28, v30, v32
	v_pk_mul_f32 v[4:5], v[4:5], v[30:31]
	v_lshlrev_b32_e32 v30, 16, v29
	v_and_b32_e32 v31, 0xffff0000, v29
	v_mul_f32_e32 v28, 0xbfb8aa3b, v30
	v_mul_f32_e32 v29, 0xbfb8aa3b, v31
	v_exp_f32_e32 v28, v28
	v_exp_f32_e32 v29, v29
	v_cvt_pk_bf16_f32 v4, v4, v5
	v_pk_add_f32 v[28:29], v[28:29], 1.0 op_sel_hi:[1,0]
	s_nop 0
	v_div_scale_f32 v32, s[0:1], v29, v29, v31
	v_rcp_f32_e32 v33, v32
	s_nop 0
	v_fma_f32 v43, -v32, v33, 1.0
	v_fmac_f32_e32 v33, v43, v33
	v_div_scale_f32 v43, vcc, v31, v29, v31
	v_mul_f32_e32 v49, v43, v33
	v_fma_f32 v50, -v32, v49, v43
	v_fmac_f32_e32 v49, v50, v33
	v_fma_f32 v32, -v32, v49, v43
	v_div_fmas_f32 v32, v32, v33, v49
	v_div_fixup_f32 v29, v32, v29, v31
	v_div_scale_f32 v31, s[0:1], v28, v28, v30
	v_rcp_f32_e32 v32, v31
	s_nop 0
	v_fma_f32 v33, -v31, v32, 1.0
	v_fmac_f32_e32 v32, v33, v32
	v_div_scale_f32 v33, vcc, v30, v28, v30
	v_mul_f32_e32 v43, v33, v32
	v_fma_f32 v49, -v31, v43, v33
	v_fmac_f32_e32 v43, v49, v32
	v_fma_f32 v31, -v31, v43, v33
	v_div_fmas_f32 v31, v31, v32, v43
	v_div_fixup_f32 v28, v31, v28, v30
	v_pk_mul_f32 v[6:7], v[6:7], v[28:29]
	s_nop 0
	v_cvt_pk_bf16_f32 v5, v6, v7
	v_lshl_add_u64 v[6:7], v[40:41], 0, v[26:27]
	global_store_dwordx2 v[6:7], v[4:5], off
	v_or_b32_e32 v4, 48, v36
	v_lshlrev_b32_e32 v6, 1, v4
	v_mov_b32_e32 v7, v9
	v_lshl_add_u64 v[26:27], v[46:47], 0, v[6:7]
	s_waitcnt vmcnt(3)
	v_mov_b64_e32 v[26:27], v[182:183]
	v_mov_b32_e32 v5, v9
	s_nop 0
	v_lshlrev_b32_e32 v30, 16, v26
	v_and_b32_e32 v26, 0xffff0000, v26
	v_mul_f32_e32 v28, 0xbfb8aa3b, v30
	v_mul_f32_e32 v29, 0xbfb8aa3b, v26
	v_exp_f32_e32 v28, v28
	v_exp_f32_e32 v29, v29
	s_nop 0
	v_pk_add_f32 v[28:29], v[28:29], 1.0 op_sel_hi:[1,0]
	s_nop 0
	v_div_scale_f32 v31, s[0:1], v29, v29, v26
	v_rcp_f32_e32 v32, v31
	s_nop 0
	v_fma_f32 v33, -v31, v32, 1.0
	v_fmac_f32_e32 v32, v33, v32
	v_div_scale_f32 v33, vcc, v26, v29, v26
	v_mul_f32_e32 v43, v33, v32
	v_fma_f32 v46, -v31, v43, v33
	v_fmac_f32_e32 v43, v46, v32
	v_fma_f32 v31, -v31, v43, v33
	v_div_fmas_f32 v31, v31, v32, v43
	v_div_fixup_f32 v29, v31, v29, v26
	v_div_scale_f32 v26, s[0:1], v28, v28, v30
	v_rcp_f32_e32 v31, v26
	s_nop 0
	v_fma_f32 v32, -v26, v31, 1.0
	v_fmac_f32_e32 v31, v32, v31
	v_div_scale_f32 v32, vcc, v30, v28, v30
	v_mul_f32_e32 v33, v32, v31
	v_fma_f32 v43, -v26, v33, v32
	v_fmac_f32_e32 v33, v43, v31
	v_fma_f32 v26, -v26, v33, v32
	v_div_fmas_f32 v26, v26, v31, v33
	v_div_fixup_f32 v28, v26, v28, v30
	v_pk_mul_f32 v[0:1], v[0:1], v[28:29]
	v_lshlrev_b32_e32 v28, 16, v27
	v_and_b32_e32 v29, 0xffff0000, v27
	v_mul_f32_e32 v26, 0xbfb8aa3b, v28
	v_mul_f32_e32 v27, 0xbfb8aa3b, v29
	v_exp_f32_e32 v26, v26
	v_exp_f32_e32 v27, v27
	v_cvt_pk_bf16_f32 v0, v0, v1
	v_pk_add_f32 v[26:27], v[26:27], 1.0 op_sel_hi:[1,0]
	s_nop 0
	v_div_scale_f32 v30, s[0:1], v27, v27, v29
	v_rcp_f32_e32 v31, v30
	s_nop 0
	v_fma_f32 v32, -v30, v31, 1.0
	v_fmac_f32_e32 v31, v32, v31
	v_div_scale_f32 v32, vcc, v29, v27, v29
	v_mul_f32_e32 v33, v32, v31
	v_fma_f32 v43, -v30, v33, v32
	v_fmac_f32_e32 v33, v43, v31
	v_fma_f32 v30, -v30, v33, v32
	v_div_fmas_f32 v30, v30, v31, v33
	v_div_fixup_f32 v27, v30, v27, v29
	v_div_scale_f32 v29, s[0:1], v26, v26, v28
	v_rcp_f32_e32 v30, v29
	s_mov_b64 s[0:1], 0
	v_fma_f32 v31, -v29, v30, 1.0
	v_fmac_f32_e32 v30, v31, v30
	v_div_scale_f32 v31, vcc, v28, v26, v28
	v_mul_f32_e32 v32, v31, v30
	v_fma_f32 v33, -v29, v32, v31
	v_fmac_f32_e32 v32, v33, v30
	v_fma_f32 v29, -v29, v32, v31
	v_div_fmas_f32 v29, v29, v30, v32
	v_div_fixup_f32 v26, v29, v26, v28
	v_pk_mul_f32 v[2:3], v[2:3], v[26:27]
	s_nop 0
	v_cvt_pk_bf16_f32 v1, v2, v3
	v_lshl_add_u64 v[2:3], v[40:41], 0, v[6:7]
	global_store_dwordx2 v[2:3], v[0:1], off
	ds_bpermute_b32 v0, v48, v135
	s_waitcnt lgkmcnt(0)
	v_add_f32_e32 v0, v135, v0
	ds_bpermute_b32 v1, v45, v0
